# up and in-proj GEMM unit order: next-unit (pm,pn) via one multiply-shift division by the constant group size (was three float-reciprocal divisions per unit)
# speedup vs baseline: 1.0109x; 1.0025x over previous
;     __host__ __device__ bool next(int i, Unit& u) const {
;         const long L = (long)i * G + c; if (L >= nwg) return false;
;         int wgid = (int)L; { const int q = nwg / NXCD, r = nwg % NXCD, xcd = wgid % NXCD, off = wgid / NXCD; wgid = (xcd < r ? xcd * (q + 1) : r * (q + 1) + (xcd - r) * q) + off; }
;         int nig = WGM * nN, nr = nNr;
;     ...
;         asm volatile("" : "+s"(nig), "+s"(nr));
;     ...
;         const int gid = wgid / nig, fm = gid * WGM, gsz = (nM - fm) < WGM ? (nM - fm) : WGM;
;         u.pm = fm + ((wgid % nig) % gsz); const int vn = (wgid % nig) / gsz; u.pn = vn % nr; u.grp = vn / nr; u.kt0 = 0; u.nkt = nktK; u.atomic = 0; return true;
.LBB0_512:
	s_ashr_i32 s22, s22, 3
	s_add_i32 s22, s23, s22
	s_mul_i32 s40, s22, 0x28f6
	s_lshr_b32 s40, s40, 20
	s_mul_i32 s41, s40, 0x64
	s_sub_i32 s41, s22, s41
	s_and_b32 s12, s41, 3
	s_lshl_b32 s40, s40, 2
	s_add_i32 s12, s12, s40
	s_lshr_b32 s22, s41, 2

;     __host__ __device__ bool next(int i, Unit& u) const {
;         const long L = (long)i * G + c; if (L >= nwg) return false;
;         int wgid = (int)L; { const int q = nwg / NXCD, r = nwg % NXCD, xcd = wgid % NXCD, off = wgid / NXCD; wgid = (xcd < r ? xcd * (q + 1) : r * (q + 1) + (xcd - r) * q) + off; }
;         int nig = WGM * nN, nr = nNr;
;     ...
;         asm volatile("" : "+s"(nig), "+s"(nr));
;     ...
;         const int gid = wgid / nig, fm = gid * WGM, gsz = (nM - fm) < WGM ? (nM - fm) : WGM;
;         u.pm = fm + ((wgid % nig) % gsz); const int vn = (wgid % nig) / gsz; u.pn = vn % nr; u.grp = vn / nr; u.kt0 = 0; u.nkt = nktK; u.atomic = 0; return true;
.LBB0_1235:
	s_add_i32 s94, s94, 1
	v_readlane_b32 s3, v253, 4
	s_mul_i32 s0, s94, s28
	s_mul_hi_u32 s1, s94, s3
	s_add_i32 s1, s1, s0
	s_mul_i32 s0, s94, s3
	s_add_u32 s0, s0, s2
	s_addc_u32 s1, s1, s27
	v_mov_b64_e32 v[4:5], s[30:31]
	v_cmp_ge_i64_e32 vcc, s[0:1], v[4:5]
	v_cmp_lt_i64_e64 s[50:51], s[0:1], v[4:5]
	s_cbranch_vccnz .LBB0_1237
	s_ashr_i32 s1, s0, 31
	s_lshr_b32 s1, s1, 29
	s_add_i32 s1, s0, s1
	s_ashr_i32 s8, s1, 3
	s_and_b32 s1, s1, -8
	s_sub_i32 s0, s0, s1
	s_lshr_b32 s1, s0, 31
	s_or_b32 s1, s80, s1
	s_mul_i32 s0, s1, s0
	s_add_i32 s0, s0, s8
	s_mul_i32 s1, s0, 0x1746
	s_lshr_b32 s1, s1, 20
	s_mul_i32 s8, s1, 0xb0
	s_sub_i32 s0, s0, s8
	s_and_b32 s8, s0, 3
	s_lshl_b32 s12, s1, 2
	s_add_i32 s12, s12, s8
	s_lshr_b32 s22, s0, 2
